# stack on sel-prio variant: DA half prologue loads issued together; DA fast path reads the first PV fragments before the second sub-tile's K fragments
# baseline (speedup 1.0000x reference)
; #define LAS __attribute__((address_space(3)))
; __device__ __forceinline__ void attn_fast_x2(float mr1, f32x16& L1, f32x16& oa0, f32x16& oa1, float mr2, f32x16& L2, f32x16& ob0, f32x16& ob1, ...
;     f32x16 s1, s2;
; #pragma unroll
;     for (int i = 0; i < 16; ++i) { s1[i] = -mr1; s2[i] = -mr2; }
; #pragma unroll
;     for (int ks = 0; ks < 2; ++ks) { const bf16x8 a1 = *(const LAS bf16x8*)(Ks + (kr0 + r) * KP + 16 * ks + 8 * h), a2 = *(const LAS bf16x8*)(Ks + (kr0 + r) * KP + 32 + 16 * ks + 8 * h);
;         s1 = __builtin_amdgcn_mfma_f32_32x32x16_bf16(a1, qf1[ks], s1, 0, 0, 0); s2 = __builtin_amdgcn_mfma_f32_32x32x16_bf16(a2, qf2[ks], s2, 0, 0, 0); }
;     if (need_mask) {
; #pragma unroll
;         for (int i = 0; i < 16; ++i) { const bool ok = (key0 + rowi32(i, h)) <= qpos; s1[i] = ok ? s1[i] : NEG; s2[i] = ok ? s2[i] : NEG; }
;     }
;     float p1[16], p2[16];
; #pragma unroll
;     for (int i = 0; i < 16; ++i) { p1[i] = ex2(s1[i]); p2[i] = ex2(s2[i]); }
;     const u32x4 onesu = {0x3f803f80u, 0x3f803f80u, 0x3f803f80u, 0x3f803f80u}; const bf16x8 ones = __builtin_bit_cast(bf16x8, onesu);
; #pragma unroll
;     for (int s2i = 0; s2i < 2; ++s2i) {
;         const bf16x8 pb1 = pack8(p1[8 * s2i + 0], p1[8 * s2i + 1], p1[8 * s2i + 2], p1[8 * s2i + 3], p1[8 * s2i + 4], p1[8 * s2i + 5], p1[8 * s2i + 6], p1[8 * s2i + 7]);
;         const bf16x8 pb2 = pack8(p2[8 * s2i + 0], p2[8 * s2i + 1], p2[8 * s2i + 2], p2[8 * s2i + 3], p2[8 * s2i + 4], p2[8 * s2i + 5], p2[8 * s2i + 6], p2[8 * s2i + 7]);
;         const LAS bf16_t* vp = Vt + r * VP + kr0 + 16 * s2i + 4 * h;
;         const u32x2 a0l = *(const LAS u32x2*)vp, a0h = *(const LAS u32x2*)(vp + 8);
;         const u32x2 a1l = *(const LAS u32x2*)(vp + 32 * VP), a1h = *(const LAS u32x2*)(vp + 32 * VP + 8);
;         const u32x4 v0 = {a0l.x, a0l.y, a0h.x, a0h.y}, v1 = {a1l.x, a1l.y, a1h.x, a1h.y};
;         oa0 = __builtin_amdgcn_mfma_f32_32x32x16_bf16(__builtin_bit_cast(bf16x8, v0), pb1, oa0, 0, 0, 0);
;         ob0 = __builtin_amdgcn_mfma_f32_32x32x16_bf16(__builtin_bit_cast(bf16x8, v0), pb2, ob0, 0, 0, 0);
;         oa1 = __builtin_amdgcn_mfma_f32_32x32x16_bf16(__builtin_bit_cast(bf16x8, v1), pb1, oa1, 0, 0, 0);
;         ob1 = __builtin_amdgcn_mfma_f32_32x32x16_bf16(__builtin_bit_cast(bf16x8, v1), pb2, ob1, 0, 0, 0);
;         L1 = __builtin_amdgcn_mfma_f32_32x32x16_bf16(ones, pb1, L1, 0, 0, 0);
.Lda_fast:
	v_lshl_add_u32 v189, v248, 1, v181
	v_lshlrev_b32_e32 v99, 1, v248
	v_add3_u32 v99, s18, v240, v99
	ds_read_b128 v[100:103], v189
	ds_read_b128 v[104:107], v189 offset:32
	ds_read_b128 v[108:111], v189 offset:64
	ds_read_b128 v[112:115], v189 offset:96
	v_lshl_add_u32 v98, v248, 1, v181
	v_add_u32_e32 v181, 0x3000, v98
	v_add_u32_e32 v98, 0x2000, v98
	s_waitcnt lgkmcnt(3)
	v_mfma_f32_32x32x16_bf16 v[116:131], v[100:103], v[152:155], v[206:221]
	s_waitcnt lgkmcnt(2)
	v_mfma_f32_32x32x16_bf16 v[116:131], v[104:107], v[156:159], v[116:131]
	s_waitcnt lgkmcnt(1)
	v_mfma_f32_32x32x16_bf16 v[132:147], v[108:111], v[160:163], v[190:205]
	s_waitcnt lgkmcnt(0)
	v_mfma_f32_32x32x16_bf16 v[132:147], v[112:115], v[148:151], v[132:147]
	ds_read_b128 v[100:103], v98 offset:1024
	ds_read_b128 v[104:107], v181 offset:1536
	ds_read_b128 v[182:185], v99
	ds_read_b128 v[226:229], v99 offset:32
	ds_read_b128 v[242:245], v99 offset:64
	ds_read_b128 v[172:175], v99 offset:96
	ds_read_b128 v[108:111], v98 offset:1056
	ds_read_b128 v[112:115], v181 offset:1568
	v_exp_f32_e32 v116, v116
	v_exp_f32_e32 v117, v117
	v_exp_f32_e32 v118, v118
	v_exp_f32_e32 v119, v119
	v_exp_f32_e32 v120, v120
	v_exp_f32_e32 v121, v121
	v_exp_f32_e32 v122, v122
	v_exp_f32_e32 v123, v123
	v_cvt_pk_bf16_f32 v116, v116, v117
	v_cvt_pk_bf16_f32 v117, v118, v119
	v_cvt_pk_bf16_f32 v118, v120, v121
	v_cvt_pk_bf16_f32 v119, v122, v123
	s_waitcnt lgkmcnt(6)
	s_nop 0
	v_mfma_f32_32x32x16_bf16 v[34:49], v[100:103], v[116:119], v[34:49]
	v_exp_f32_e32 v124, v124
	v_exp_f32_e32 v125, v125
	v_exp_f32_e32 v126, v126
	v_mfma_f32_32x32x16_bf16 v[66:81], v[104:107], v[116:119], v[66:81]
	v_exp_f32_e32 v127, v127
	v_exp_f32_e32 v128, v128
	v_exp_f32_e32 v129, v129
	v_mfma_f32_32x32x16_bf16 v[2:17], v[222:225], v[116:119], v[2:17]
	v_exp_f32_e32 v130, v130
	v_exp_f32_e32 v131, v131
	v_cvt_pk_bf16_f32 v120, v124, v125
	v_cvt_pk_bf16_f32 v121, v126, v127
	v_cvt_pk_bf16_f32 v122, v128, v129
	v_cvt_pk_bf16_f32 v123, v130, v131
	s_waitcnt lgkmcnt(0)
	s_nop 0
	v_mfma_f32_32x32x16_bf16 v[34:49], v[108:111], v[120:123], v[34:49]
	v_exp_f32_e32 v132, v132
	v_exp_f32_e32 v133, v133
	v_exp_f32_e32 v134, v134
	v_mfma_f32_32x32x16_bf16 v[66:81], v[112:115], v[120:123], v[66:81]
	v_exp_f32_e32 v135, v135
	v_exp_f32_e32 v136, v136
	v_exp_f32_e32 v137, v137
	v_mfma_f32_32x32x16_bf16 v[2:17], v[222:225], v[120:123], v[2:17]
	v_exp_f32_e32 v138, v138
	v_exp_f32_e32 v139, v139
	v_cvt_pk_bf16_f32 v132, v132, v133
	v_cvt_pk_bf16_f32 v133, v134, v135
	v_mfma_f32_32x32x16_bf16 v[116:131], v[182:185], v[152:155], v[206:221]
	v_cvt_pk_bf16_f32 v134, v136, v137
	v_cvt_pk_bf16_f32 v135, v138, v139
	v_exp_f32_e32 v140, v140
	v_exp_f32_e32 v141, v141
	v_mfma_f32_32x32x16_bf16 v[116:131], v[226:229], v[156:159], v[116:131]
	v_exp_f32_e32 v142, v142
	v_exp_f32_e32 v143, v143
	v_exp_f32_e32 v144, v144
	ds_read_b128 v[182:185], v98 offset:1088
	ds_read_b128 v[226:229], v181 offset:1600
	v_mfma_f32_32x32x16_bf16 v[82:97], v[100:103], v[132:135], v[82:97]
	v_exp_f32_e32 v145, v145
	v_exp_f32_e32 v146, v146
	v_exp_f32_e32 v147, v147
	v_mfma_f32_32x32x16_bf16 v[50:65], v[104:107], v[132:135], v[50:65]
	v_cvt_pk_bf16_f32 v136, v140, v141
	v_cvt_pk_bf16_f32 v137, v142, v143
	v_cvt_pk_bf16_f32 v138, v144, v145
	v_cvt_pk_bf16_f32 v139, v146, v147
	ds_read_b128 v[100:103], v98 offset:1120
	ds_read_b128 v[104:107], v181 offset:1632
	v_mfma_f32_32x32x16_bf16 v[18:33], v[222:225], v[132:135], v[18:33]
	v_exp_f32_e32 v116, v116
	v_exp_f32_e32 v117, v117
	v_exp_f32_e32 v118, v118
	v_mfma_f32_32x32x16_bf16 v[82:97], v[108:111], v[136:139], v[82:97]
	v_exp_f32_e32 v119, v119
	v_exp_f32_e32 v120, v120
	v_exp_f32_e32 v121, v121
	v_mfma_f32_32x32x16_bf16 v[50:65], v[112:115], v[136:139], v[50:65]
	v_exp_f32_e32 v122, v122
	v_exp_f32_e32 v123, v123
	v_cvt_pk_bf16_f32 v116, v116, v117
	v_cvt_pk_bf16_f32 v117, v118, v119
	v_mfma_f32_32x32x16_bf16 v[18:33], v[222:225], v[136:139], v[18:33]
	v_cvt_pk_bf16_f32 v118, v120, v121
	v_cvt_pk_bf16_f32 v119, v122, v123
	v_exp_f32_e32 v124, v124
	v_exp_f32_e32 v125, v125
	v_mfma_f32_32x32x16_bf16 v[132:147], v[242:245], v[160:163], v[190:205]
	v_exp_f32_e32 v126, v126
	v_exp_f32_e32 v127, v127
	v_exp_f32_e32 v128, v128
	v_mfma_f32_32x32x16_bf16 v[132:147], v[172:175], v[148:151], v[132:147]
	v_exp_f32_e32 v129, v129
	v_exp_f32_e32 v130, v130
	v_exp_f32_e32 v131, v131
	s_waitcnt lgkmcnt(2)
	v_mfma_f32_32x32x16_bf16 v[34:49], v[182:185], v[116:119], v[34:49]
	v_cvt_pk_bf16_f32 v120, v124, v125
	v_cvt_pk_bf16_f32 v121, v126, v127
	v_cvt_pk_bf16_f32 v122, v128, v129
	v_cvt_pk_bf16_f32 v123, v130, v131
	v_mfma_f32_32x32x16_bf16 v[66:81], v[226:229], v[116:119], v[66:81]
	s_nop 1
	v_exp_f32_e32 v132, v132
	v_exp_f32_e32 v133, v133
	v_exp_f32_e32 v134, v134
	v_mfma_f32_32x32x16_bf16 v[2:17], v[222:225], v[116:119], v[2:17]
	v_exp_f32_e32 v135, v135
	v_exp_f32_e32 v136, v136
	v_exp_f32_e32 v137, v137
	s_waitcnt lgkmcnt(0)
	v_mfma_f32_32x32x16_bf16 v[34:49], v[100:103], v[120:123], v[34:49]
	v_exp_f32_e32 v138, v138
	v_exp_f32_e32 v139, v139
	v_cvt_pk_bf16_f32 v132, v132, v133
	v_cvt_pk_bf16_f32 v133, v134, v135
	v_mfma_f32_32x32x16_bf16 v[66:81], v[104:107], v[120:123], v[66:81]
	v_cvt_pk_bf16_f32 v134, v136, v137
	v_cvt_pk_bf16_f32 v135, v138, v139
	v_exp_f32_e32 v140, v140
	v_exp_f32_e32 v141, v141
	v_mfma_f32_32x32x16_bf16 v[2:17], v[222:225], v[120:123], v[2:17]
	v_exp_f32_e32 v142, v142
	v_exp_f32_e32 v143, v143
	v_exp_f32_e32 v144, v144
	v_mfma_f32_32x32x16_bf16 v[18:33], v[222:225], v[132:135], v[18:33]
	v_exp_f32_e32 v145, v145
	v_exp_f32_e32 v146, v146
	v_exp_f32_e32 v147, v147
	v_mfma_f32_32x32x16_bf16 v[82:97], v[182:185], v[132:135], v[82:97]
	v_cvt_pk_bf16_f32 v136, v140, v141
	v_cvt_pk_bf16_f32 v137, v142, v143
	v_cvt_pk_bf16_f32 v138, v144, v145
	v_cvt_pk_bf16_f32 v139, v146, v147
	v_mfma_f32_32x32x16_bf16 v[50:65], v[226:229], v[132:135], v[50:65]
	s_nop 0
	v_mfma_f32_32x32x16_bf16 v[18:33], v[222:225], v[136:139], v[18:33]
	v_mfma_f32_32x32x16_bf16 v[82:97], v[100:103], v[136:139], v[82:97]
	v_mfma_f32_32x32x16_bf16 v[50:65], v[104:107], v[136:139], v[50:65]
	s_xor_b32 s24, s20, 1
	s_mul_i32 s24, s24, 0x4800
	v_add3_u32 v189, s24, v249, v238
	s_waitcnt vmcnt(1)
	ds_write_b128 v189, v[168:171]
	v_lshl_add_u32 v189, v251, 1, s24
	s_waitcnt vmcnt(0)
	ds_write_b16 v189, v164 offset:9216
	ds_write_b16_d16_hi v189, v164 offset:9360
	ds_write_b16 v189, v165 offset:9504
	ds_write_b16_d16_hi v189, v165 offset:9648
	ds_write_b16 v189, v166 offset:9792
	ds_write_b16_d16_hi v189, v166 offset:9936
	ds_write_b16 v189, v167 offset:10080
	v_lshl_add_u32 v189, v239, 1, s24
	s_cmp_ge_u32 s21, s6
	ds_write_b16_d16_hi v189, v167 offset:9216
	s_cbranch_scc1 .Lda_fast_nofetch
	global_load_dwordx4 v[168:171], v[234:235], off
	global_load_dwordx4 v[164:167], v[236:237], off
